# baseline (speedup 1.0000x reference)
; __device__ __forceinline__ void lds_barrier() { asm volatile("s_waitcnt lgkmcnt(0)" ::: "memory"); __builtin_amdgcn_s_barrier(); asm volatile("" ::: "memory"); }
; __device__ __forceinline__ gbyte_t* launder(unsigned char* q) { gbyte_t* g = (gbyte_t*)q; asm volatile("" : "+s"(g)); return g; }
;     __device__ __forceinline__ bf16_t* u(int n) const { return (bf16_t*)(ws + WS_ARENA + (size_t)n * UNIT); }
; __device__ __forceinline__ void wkv_phase(const WkvT& W, unsigned char* lds) {
;     const int tid = threadIdx.x, lane = tid & 63, wave = tid >> 6;
;     float* sP = (float*)lds; float* sV = sP + 2 * 12288; float* sY = sV + 1024;
;     for (int unit = blockIdx.x; unit < 256; unit += gridDim.x) {
;         const int q = (unit >> 3) & 3, hb = (unit & 7) + 8 * (unit >> 5), b = hb >> 5, h = hb & 31;
;         const size_t rowbase = (size_t)b * SEQ; const int cbase = h * 64;
;         float kkc[4], kac[4], rkc[4]; WkvRaw raw;
; #pragma unroll
;         for (int e = 0; e < 4; ++e) { const int j = cbase + 4 * (tid & 15) + e; kkc[e] = W.kk[j]; kac[e] = W.ka[j]; rkc[e] = W.rk[j]; }
;         f32x2 S = {0.f, 0.f};
;         const int il = 2 * wave + (lane >> 5), jj = lane & 31;
;         __syncthreads();
;         wkv_issue(W, raw, rowbase, cbase, q, 0, tid);
;         wkv_stage(W, raw, rowbase, h, q, 0, tid, kkc, kac, rkc, sP, sV);
;         lds_barrier();
; __device__ __forceinline__ void ph14(const Params& p, unsigned char* lds) {
;     const Lay L{launder(p.ws)};
;     WkvT W{L.u(0), L.u(4), L.u(22), L.u(8), L.u(12), p.in[27], p.in[28], p.in[29], L.u(16), (float*)L.u(26), (float*)L.u(27)};
.LBB0_1610:
	s_cmp_lt_i32 s84, 15
	s_cselect_b64 s[48:49], -1, 0
	s_and_b64 s[0:1], s[48:49], s[0:1]
	s_andn2_b64 vcc, exec, s[0:1]
	s_cbranch_vccnz .LBB0_1647
	v_readfirstlane_b32 s99, v0
	s_mov_b64 s[52:53], s[78:79]
	s_cmpk_gt_i32 s2, 0xff
	s_cbranch_scc1 .LBB0_1647
	s_add_u32 s54, s52, 0x3500000
	s_addc_u32 s55, s53, 0
	s_add_u32 s56, s52, 0x7500000
	s_addc_u32 s57, s53, 0
	s_add_u32 s68, s52, 0x19500000
	s_addc_u32 s69, s53, 0
	s_add_u32 s86, s52, 0xb500000
	s_addc_u32 s87, s53, 0
	s_add_u32 s88, s52, 0xf500000
	s_addc_u32 s89, s53, 0
	s_add_u32 s90, s52, 0x1e500000
	v_and_b32_e32 v18, 15, v0
	v_and_b32_e32 v4, 0x1f0, v0
	s_addc_u32 s91, s53, 0
	s_add_i32 s3, 0, 0x18000
	v_lshlrev_b32_e32 v4, 2, v4
	v_lshlrev_b32_e32 v5, 4, v18
	v_add3_u32 v15, s3, v4, v5
	v_lshrrev_b32_e32 v5, 3, v0
	v_and_b32_e32 v5, 60, v5
	v_and_b32_e32 v6, 16, v0
	v_and_b32_e32 v2, 31, v0
	v_lshrrev_b32_e32 v14, 4, v0
	v_lshlrev_b32_e32 v20, 2, v18
	v_add_u32_e32 v21, s3, v5
	v_cmp_ne_u32_e64 s[4:5], 0, v6
	v_lshlrev_b32_e32 v6, 6, v18
	s_add_i32 s3, 0, 0x19000
	v_lshlrev_b32_e32 v1, 2, v0
	v_mov_b32_e32 v17, 0
	v_mul_u32_u24_e32 v3, 0x60, v0
	v_mad_u32_u24 v19, v2, 48, 0
	v_cmp_eq_u32_e64 s[6:7], 31, v2
	s_waitcnt vmcnt(1)
	v_add3_u32 v29, s3, v6, v5
	v_add3_u32 v60, s3, v4, v20
	v_cmp_eq_u32_e64 s[10:11], 16, v2
	v_cmp_eq_u32_e64 s[12:13], 17, v2
	v_cmp_eq_u32_e64 s[14:15], 18, v2
	v_cmp_eq_u32_e64 s[16:17], 19, v2
	v_cmp_eq_u32_e64 s[18:19], 20, v2
	v_cmp_eq_u32_e64 s[20:21], 21, v2
	v_cmp_eq_u32_e64 s[22:23], 22, v2
	v_cmp_eq_u32_e64 s[24:25], 23, v2
	v_cmp_eq_u32_e64 s[26:27], 24, v2
	v_cmp_eq_u32_e64 s[28:29], 25, v2
	v_cmp_eq_u32_e64 s[30:31], 26, v2
	v_cmp_eq_u32_e64 s[34:35], 27, v2
	v_cmp_eq_u32_e64 s[36:37], 28, v2
	v_cmp_eq_u32_e64 s[38:39], 29, v2
	v_cmp_eq_u32_e64 s[40:41], 30, v2
	v_and_b32_e32 v243, 8, v0
	v_cmp_ne_u32_e64 s[10:11], 0, v243
	v_and_b32_e32 v243, 4, v0
	v_cmp_ne_u32_e64 s[12:13], 0, v243
	v_and_b32_e32 v243, 2, v0
	v_cmp_ne_u32_e64 s[14:15], 0, v243
	v_and_b32_e32 v243, 1, v0
	v_cmp_ne_u32_e64 s[16:17], 0, v243
	v_readfirstlane_b32 s99, v0
	v_mul_u32_u24_e32 v182, 0x60, v18
	v_and_b32_e32 v188, 8, v18
	v_mul_u32_u24_e32 v183, 0xc0, v18
	v_mad_u32_u24 v182, v188, 2, v182
	v_add_u32_e32 v183, 16, v183
	v_lshrrev_b32_e32 v188, 4, v0
	v_sub_u32_e32 v183, v183, v182
	v_lshlrev_b32_e32 v188, 2, v188
	v_add_u32_e32 v184, 0x10200, v182
	v_add_u32_e32 v186, 0x18000, v188
	v_add_u32_e32 v185, 0x10200, v183
	v_lshl_add_u32 v187, v18, 6, v188
	v_add_u32_e32 v187, 0x19000, v187
	v_add_u32_e32 v189, 0x400, v186
	v_add_u32_e32 v226, 0x800, v186
	v_add_u32_e32 v227, 0xc00, v186
	v_mul_u32_u24_e32 v155, 0x60, v18
	v_add_u32_e32 v155, 64, v155
	v_and_b32_e32 v188, 8, v18
	v_lshl_add_u32 v155, v188, 1, v155
	v_add_u32_e32 v188, 0x10200, v155
	v_lshlrev_b32_e32 v2, 12, v14
	v_lshlrev_b32_e32 v4, 1, v18
	s_mov_b32 s3, 0x13500000
	v_and_b32_e32 v1, 60, v1
	v_cmp_gt_u32_e64 s[0:1], 4, v18
	s_mov_b32 s93, 0
	v_cmp_eq_u32_e64 s[8:9], 0, v18
	v_add_u32_e32 v61, 0x10200, v19
	v_add_u32_e32 v62, 0x10220, v19
	v_add_u32_e32 v63, 0x10210, v19
	v_add_u32_e32 v64, 0x10800, v19
	v_add_u32_e32 v65, 0x10820, v19
	v_add_u32_e32 v66, 0x10810, v19
	v_add_u32_e32 v67, 0x10e00, v19
	v_add_u32_e32 v68, 0x10e20, v19
	v_add_u32_e32 v69, 0x10e10, v19
	v_add_u32_e32 v70, 0x11400, v19
	v_add_u32_e32 v71, 0x11420, v19
	v_add_u32_e32 v72, 0x11410, v19
	v_add_u32_e32 v73, 0x11a00, v19
	v_add_u32_e32 v74, 0x11a20, v19
	v_add_u32_e32 v75, 0x11a10, v19
	v_add_u32_e32 v76, 0x12000, v19
	v_add_u32_e32 v77, 0x12020, v19
	v_add_u32_e32 v78, 0x12010, v19
	v_add_u32_e32 v79, 0x12600, v19
	v_add_u32_e32 v80, 0x12620, v19
	v_add_u32_e32 v81, 0x12610, v19
	v_add_u32_e32 v82, 0x12c00, v19
	v_add_u32_e32 v83, 0x12c20, v19
	v_add_u32_e32 v84, 0x12c10, v19
	v_add_u32_e32 v85, 0x13200, v19
	v_add_u32_e32 v86, 0x13220, v19
	v_add_u32_e32 v87, 0x13210, v19
	v_add_u32_e32 v88, 0x13800, v19
	v_add_u32_e32 v89, 0x13820, v19
	s_waitcnt vmcnt(0)
	v_add_u32_e32 v90, 0x13810, v19
	v_add_u32_e32 v91, 0x13e00, v19
	v_add_u32_e32 v92, 0x13e20, v19
	v_add_u32_e32 v93, 0x13e10, v19
	v_add_u32_e32 v94, 0x14400, v19
	v_add_u32_e32 v95, 0x14420, v19
	v_add_u32_e32 v96, 0x14410, v19
	v_add_u32_e32 v97, 0x14a00, v19
	v_add_u32_e32 v98, 0x14a20, v19
	v_add_u32_e32 v99, 0x14a10, v19
	v_add_u32_e32 v100, 0x15000, v19
	v_add_u32_e32 v101, 0x15020, v19
	v_add_u32_e32 v102, 0x15010, v19
	v_add_u32_e32 v103, 0x15600, v19
	v_add_u32_e32 v104, 0x15620, v19
	v_add_u32_e32 v105, 0x15610, v19
	v_add_u32_e32 v106, 0x15c00, v19
	v_add_u32_e32 v107, 0x15c20, v19
	v_add_u32_e32 v108, 0x15c10, v19
	v_add_u32_e32 v109, 0x16200, v19
	v_add_u32_e32 v110, 0x16220, v19
	v_add_u32_e32 v111, 0x16210, v19
	v_add_u32_e32 v112, 0x16800, v19
	v_add_u32_e32 v113, 0x16820, v19
	v_add_u32_e32 v114, 0x16810, v19
	v_add_u32_e32 v115, 0x16e00, v19
	v_add_u32_e32 v116, 0x16e20, v19
	v_add_u32_e32 v117, 0x16e10, v19
	v_add_u32_e32 v118, 0x17400, v19
	v_add_u32_e32 v119, 0x17420, v19
	v_add_u32_e32 v120, 0x17410, v19
	v_add_u32_e32 v121, 0x17a00, v19
	v_add_u32_e32 v122, 0x17a20, v19
	v_add_u32_e32 v123, 0x17a10, v19
	v_lshlrev_b32_e32 v22, 10, v14
	v_mov_b32_e32 v23, v17
	v_or_b32_e32 v24, 0x13520000, v2
	v_mov_b32_e32 v25, v17
	v_lshlrev_b32_e32 v26, 7, v14
	v_mov_b32_e32 v27, v17
	v_lshl_or_b32 v28, v18, 3, v2
	v_or3_b32 v30, v2, v4, s3
	v_mov_b32_e32 v31, v17
	s_mov_b32 s3, 0xf800000
	v_mov_b32_e32 v124, 0x260
	s_mov_b64 s[94:95], 0x40000
	v_add_u32_e32 v125, 0, v3
	s_mov_b32 s44, s2
	s_mov_b32 s45, s2
	s_branch .LBB0_1614

; __device__ __forceinline__ float bflo(unsigned w) { return __uint_as_float(w << 16); }
; __device__ __forceinline__ float bfhi(unsigned w) { return __uint_as_float(w & 0xffff0000u); }
; __device__ __forceinline__ float row16_sum(float x) { x += dpp_f(x, 0); x += dpp_f(x, 1); x += dpp_f(x, 2); x += dpp_f(x, 3); return x; }
; __device__ __forceinline__ void wkv_stage(const WkvT& W, const WkvRaw& raw, size_t rowbase, int h, int q, int c, int tid, const float (&kkc)[4], const float (&kac)[4], const float (&rkc)[4],
;                                           float* sP, float* sV) {
;     const float r[4] = {bflo(raw.r[0]), bfhi(raw.r[0]), bflo(raw.r[1]), bfhi(raw.r[1])}, k[4] = {bflo(raw.k[0]), bfhi(raw.k[0]), bflo(raw.k[1]), bfhi(raw.k[1])};
;     const float a[4] = {bflo(raw.a[0]), bfhi(raw.a[0]), bflo(raw.a[1]), bfhi(raw.a[1])}, l[4] = {bflo(raw.l[0]), bfhi(raw.l[0]), bflo(raw.l[1]), bfhi(raw.l[1])};
;     float kkr[4], km[4], n2 = 0.f, bs = 0.f;
; #pragma unroll
;     for (int e = 0; e < 4; ++e) { kkr[e] = k[e] * kkc[e]; n2 += kkr[e] * kkr[e]; km[e] = k[e] * (1.f + (a[e] - 1.f) * kac[e]); bs += r[e] * km[e] * rkc[e]; }
;     n2 = row16_sum(n2); bs = row16_sum(bs);
;     const float inv = __builtin_amdgcn_rcpf(fmaxf(sqrtf(n2), 1e-12f));
;     const int t = tid >> 4;
;     float* rec = sP + (t * 32 + 2 * (tid & 15)) * 12;
; #pragma unroll
;     for (int hlf = 0; hlf < 2; ++hlf) { const int e = 2 * hlf; float* rp = rec + hlf * 12;
;         *(f32x4*)(rp) = (f32x4){-kkr[e] * inv, -kkr[e + 1] * inv, __builtin_amdgcn_exp2f(LOG2E_ * l[e]), __builtin_amdgcn_exp2f(LOG2E_ * l[e + 1])};
;         *(f32x4*)(rp + 4) = (f32x4){kkr[e] * inv * a[e], kkr[e + 1] * inv * a[e + 1], km[e], km[e + 1]};
;         *(f32x2*)(rp + 8) = (f32x2){r[e], r[e + 1]}; }
;     if ((tid & 15) < 4) *(f32x4*)(sV + t * 16 + 4 * (tid & 15)) = (f32x4){bflo(raw.v[0]), bfhi(raw.v[0]), bflo(raw.v[1]), bfhi(raw.v[1])};
;     if (q == 0 && (tid & 15) == 0) W.bonus[(rowbase + (size_t)c * 32 + t) * 32 + h] = bs;
; }
.LBB0_1616:
	s_or_b64 exec, exec, s[42:43]
	s_waitcnt vmcnt(2)
	v_lshlrev_b32_e32 v54, 16, v42
	v_and_b32_e32 v55, 0xffff0000, v42
	v_and_b32_e32 v49, 0xffff0000, v43
	v_lshlrev_b32_e32 v48, 16, v43
	v_pk_mul_f32 v[42:43], v[6:7], v[54:55]
	v_pk_mul_f32 v[50:51], v[8:9], v[48:49]
	v_pk_mul_f32 v[56:57], v[42:43], v[42:43]
	v_pk_mul_f32 v[52:53], v[50:51], v[50:51]
	v_add_f32_e32 v16, v56, v57
	v_add_f32_e32 v16, v52, v16
	v_add_f32_e32 v16, v53, v16
	v_lshlrev_b32_e32 v44, 16, v40
	v_and_b32_e32 v45, 0xffff0000, v40
	v_add_f32_dpp v16, v16, v16 quad_perm:[1,0,3,2] row_mask:0xf bank_mask:0xf bound_ctrl:1
	v_lshlrev_b32_e32 v46, 16, v41
	v_and_b32_e32 v47, 0xffff0000, v41
	v_add_f32_dpp v16, v16, v16 quad_perm:[2,3,0,1] row_mask:0xf bank_mask:0xf bound_ctrl:1
	s_waitcnt vmcnt(0)
	v_lshlrev_b32_e32 v41, 16, v38
	v_and_b32_e32 v38, 0xffff0000, v38
	v_add_f32_dpp v16, v16, v16 row_half_mirror row_mask:0xf bank_mask:0xf bound_ctrl:1
	s_nop 1
	v_add_f32_dpp v16, v16, v16 row_mirror row_mask:0xf bank_mask:0xf bound_ctrl:1
	v_mul_f32_e32 v40, 0x4f800000, v16
	v_cmp_gt_f32_e32 vcc, s3, v16
	s_nop 1
	v_cndmask_b32_e32 v16, v16, v40, vcc
	v_sqrt_f32_e32 v40, v16
	s_nop 0
	v_add_u32_e32 v52, -1, v40
	v_fma_f32 v53, -v52, v40, v16
	v_cmp_ge_f32_e64 s[42:43], 0, v53
	v_add_u32_e32 v53, 1, v40
	s_nop 0
	v_cndmask_b32_e64 v52, v40, v52, s[42:43]
	v_fma_f32 v40, -v53, v40, v16
	v_cmp_lt_f32_e64 s[42:43], 0, v40
	s_nop 1
	v_cndmask_b32_e64 v40, v52, v53, s[42:43]
	v_mul_f32_e32 v52, 0x37800000, v40
	v_cndmask_b32_e32 v40, v40, v52, vcc
	v_cmp_class_f32_e32 vcc, v16, v124
	v_and_b32_e32 v53, 0xffff0000, v39
	s_nop 0
	v_cndmask_b32_e32 v16, v40, v16, vcc
	v_max_f32_e32 v16, 0x2b8cbccc, v16
	v_rcp_f32_e32 v52, v16
	v_mul_f32_e32 v16, 0x3fb8aa3b, v41
	v_exp_f32_e32 v40, v16
	v_mul_f32_e32 v16, 0x3fb8aa3b, v38
	v_exp_f32_e32 v41, v16
	v_lshlrev_b32_e32 v16, 16, v39
	v_pk_mul_f32 v[38:39], v[52:53], v[42:43] op_sel_hi:[0,1] neg_lo:[0,1] neg_hi:[0,1]
	v_mul_f32_e32 v16, 0x3fb8aa3b, v16
	ds_write_b128 v125, v[38:41]
	v_lshlrev_b32_e32 v38, 16, v36
	v_and_b32_e32 v39, 0xffff0000, v36
	v_pk_add_f32 v[40:41], v[38:39], -1.0 op_sel_hi:[1,0]
	s_nop 0
	v_pk_fma_f32 v[40:41], v[10:11], v[40:41], 1.0 op_sel_hi:[1,1,0]
	s_nop 0
	v_pk_mul_f32 v[40:41], v[40:41], v[54:55]
	v_pk_mul_f32 v[54:55], v[42:43], v[52:53] op_sel_hi:[1,0]
	v_exp_f32_e32 v42, v16
	v_mul_f32_e32 v16, 0x3fb8aa3b, v53
	v_mul_f32_e32 v36, v40, v44
	v_exp_f32_e32 v43, v16
	v_pk_mul_f32 v[38:39], v[54:55], v[38:39]
	v_fma_f32 v56, v2, v36, 0
	v_mul_f32_e32 v36, v41, v45
	ds_write_b128 v125, v[38:41] offset:32
	v_lshlrev_b32_e32 v38, 16, v37
	v_and_b32_e32 v39, 0xffff0000, v37
	v_fmac_f32_e32 v56, v3, v36
	v_pk_add_f32 v[36:37], v[38:39], -1.0 op_sel_hi:[1,0]
	v_pk_mul_f32 v[40:41], v[52:53], v[50:51] op_sel_hi:[0,1] neg_lo:[0,1] neg_hi:[0,1]
	v_pk_fma_f32 v[36:37], v[12:13], v[36:37], 1.0 op_sel_hi:[1,1,0]
	ds_write_b128 v125, v[40:43] offset:16
	v_pk_mul_f32 v[40:41], v[36:37], v[48:49]
	v_pk_mul_f32 v[42:43], v[50:51], v[52:53] op_sel_hi:[1,0]
	v_mul_f32_e32 v16, v40, v46
	v_mul_f32_e32 v36, v41, v47
	v_fmac_f32_e32 v56, v4, v16
	v_fmac_f32_e32 v56, v5, v36
	v_pk_mul_f32 v[38:39], v[42:43], v[38:39]
	ds_write_b128 v125, v[38:41] offset:48
	v_and_b32_e32 v236, 8, v18
	v_add_u32_e32 v237, 0x48, v125
	v_add_u32_e32 v237, v237, v236
	v_mad_u32_u24 v236, v236, 3, v125
	v_add_u32_e32 v236, 64, v236
	ds_write_b64 v236, v[44:45]
	ds_write_b64 v237, v[46:47]
	v_add_f32_dpp v16, v56, v56 quad_perm:[1,0,3,2] row_mask:0xf bank_mask:0xf bound_ctrl:1
	s_nop 1
	v_add_f32_dpp v16, v16, v16 quad_perm:[2,3,0,1] row_mask:0xf bank_mask:0xf bound_ctrl:1
	s_nop 1
	v_add_f32_dpp v16, v16, v16 row_half_mirror row_mask:0xf bank_mask:0xf bound_ctrl:1
	s_nop 1
	v_mov_b32_dpp v36, v16 row_mirror row_mask:0xf bank_mask:0xf bound_ctrl:1
	s_and_saveexec_b64 s[42:43], s[0:1]
	v_lshlrev_b32_e32 v38, 16, v32
	v_and_b32_e32 v39, 0xffff0000, v32
	v_lshlrev_b32_e32 v40, 16, v33
	v_and_b32_e32 v41, 0xffff0000, v33
	ds_write_b128 v15, v[38:41]
	s_or_b64 exec, exec, s[42:43]
	v_or_b32_e32 v37, s81, v18
	v_cmp_eq_u32_e64 s[42:43], 0, v37
	s_and_saveexec_b64 s[96:97], s[42:43]
	s_cbranch_execz .LBB0_1620
	v_lshlrev_b64 v[34:35], 7, v[34:35]
	v_lshl_add_u64 v[34:35], s[90:91], 0, v[34:35]
	s_lshl_b32 s92, s80, 2
	v_add_f32_e32 v16, v16, v36
	v_lshl_add_u64 v[34:35], v[34:35], 0, s[92:93]
	global_store_dword v[34:35], v16, off
